# nt also on the once-read Q fragments in the attention phase
# baseline (speedup 1.0000x reference)
; __device__ __forceinline__ void attn_wave(LAS unsigned char* wl, const bf16* Q, const bf16* K, const bf16* V, bf16* O, const float* relb, int b, int n, int h, int lane) {
;     ...
;     const size_t tq0 = (size_t)b * SEQ + (size_t)n * 64;
;     bf16x8 qf[2][4];
; #pragma unroll
;     for (int qb = 0; qb < 2; ++qb)
; #pragma unroll
;         for (int ks = 0; ks < 4; ++ks) qf[qb][ks] = *(const bf16x8*)(Q + (tq0 + 32 * qb + r32) * AW + h * 64 + 16 * ks + 8 * hf);
;     f32x16 o[2][2];
; #pragma unroll
;     for (int db = 0; db < 2; ++db)
; #pragma unroll
;         for (int qb = 0; qb < 2; ++qb)
; #pragma unroll
;             for (int i = 0; i < 16; ++i) o[db][qb][i] = 0.f;
;     float mrun[2] = {-INFINITY, -INFINITY}, lrun[2] = {0.f, 0.f};
;     const float CL2 = 0.125f * 1.4426950408889634f;
;     const int kk0 = n >= 8 ? 0 : 2 * (8 - n);
;     const bf16* kp = K + ((size_t)b * SEQ + (size_t)(n - 8) * 64 + r32) * AW + h * 64 + 8 * hf;
;     const bf16* vp = V + ((size_t)b * SEQ + (size_t)(n - 8) * 64 + (lane >> 3)) * AW + h * 64 + 8 * (lane & 7);
;     bf16x8 kf[4]; v4u vr[4];
; #pragma unroll
;     for (int ks = 0; ks < 4; ++ks) kf[ks] = *(const bf16x8*)(kp + (size_t)kk0 * 32 * AW + 16 * ks);
; #pragma unroll
;     for (int i = 0; i < 4; ++i) vr[i] = *(const v4u*)(vp + ((size_t)kk0 * 32 + 8 * i) * AW);
; __global__ void __launch_bounds__(512, 2) hybrid_fwd(Args args) {
;     ...
;             const int unit = (u0 & 7) * (BATCH * NCHUNK / 8) + (u0 >> 3);
;             const int b = unit / NCHUNK, n = unit % NCHUNK;
;             attn_wave(lds + wave * 8192, QB, KB, VB, ATT, rel_bias, b, n, wave, lane);
.LBB0_553:
	s_or_b64 exec, exec, s[0:1]
	s_lshl_b32 s0, s80, 5
	s_and_b32 s0, s0, 0xe0
	s_ashr_i32 s1, s80, 3
	s_add_i32 s0, s0, s1
	s_ashr_i32 s1, s0, 31
	s_lshr_b32 s1, s1, 25
	s_add_i32 s1, s0, s1
	s_ashr_i32 s14, s1, 7
	s_and_b32 s1, s1, 0xffffff80
	s_sub_i32 s16, s0, s1
	s_ashr_i32 s15, s14, 31
	s_ashr_i32 s17, s16, 31
	s_lshl_b64 s[0:1], s[14:15], 13
	s_lshl_b64 s[18:19], s[16:17], 6
	s_add_u32 s17, s18, s0
	s_addc_u32 s20, s19, s1
	s_lshl_b32 s21, s16, 1
	s_sub_i32 s21, 16, s21
	s_cmp_lt_i32 s16, 8
	v_mov_b32_e32 v1, s20
	v_or_b32_e32 v0, s17, v164
	s_cselect_b32 s44, s21, 0
	v_lshlrev_b64 v[186:187], 10, v[0:1]
	v_mov_b32_e32 v189, 0
	s_cmp_lt_i32 s44, 18
	v_mov_b32_e32 v188, 0
	v_mov_b32_e32 v63, 0
	v_mov_b32_e32 v62, 0
	v_mov_b32_e32 v61, 0
	v_mov_b32_e32 v60, 0
	v_mov_b32_e32 v59, 0
	v_mov_b32_e32 v58, 0
	v_mov_b32_e32 v57, 0
	v_mov_b32_e32 v56, 0
	v_mov_b32_e32 v55, 0
	v_mov_b32_e32 v54, 0
	v_mov_b32_e32 v53, 0
	v_mov_b32_e32 v52, 0
	v_mov_b32_e32 v51, 0
	v_mov_b32_e32 v50, 0
	v_mov_b32_e32 v49, 0
	v_mov_b32_e32 v48, 0
	v_mov_b32_e32 v31, 0
	v_mov_b32_e32 v30, 0
	v_mov_b32_e32 v29, 0
	v_mov_b32_e32 v28, 0
	v_mov_b32_e32 v27, 0
	v_mov_b32_e32 v26, 0
	v_mov_b32_e32 v25, 0
	v_mov_b32_e32 v24, 0
	v_mov_b32_e32 v23, 0
	v_mov_b32_e32 v22, 0
	v_mov_b32_e32 v21, 0
	v_mov_b32_e32 v20, 0
	v_mov_b32_e32 v19, 0
	v_mov_b32_e32 v18, 0
	v_mov_b32_e32 v17, 0
	v_mov_b32_e32 v16, 0
	v_mov_b32_e32 v47, 0
	v_mov_b32_e32 v46, 0
	v_mov_b32_e32 v45, 0
	v_mov_b32_e32 v44, 0
	v_mov_b32_e32 v43, 0
	v_mov_b32_e32 v42, 0
	v_mov_b32_e32 v41, 0
	v_mov_b32_e32 v40, 0
	v_mov_b32_e32 v39, 0
	v_mov_b32_e32 v38, 0
	v_mov_b32_e32 v37, 0
	v_mov_b32_e32 v36, 0
	v_mov_b32_e32 v35, 0
	v_mov_b32_e32 v34, 0
	v_mov_b32_e32 v33, 0
	v_mov_b32_e32 v32, 0
	v_mov_b32_e32 v15, 0
	v_mov_b32_e32 v14, 0
	v_mov_b32_e32 v13, 0
	v_mov_b32_e32 v12, 0
	v_mov_b32_e32 v11, 0
	v_mov_b32_e32 v10, 0
	v_mov_b32_e32 v9, 0
	v_mov_b32_e32 v8, 0
	v_mov_b32_e32 v7, 0
	v_mov_b32_e32 v6, 0
	v_mov_b32_e32 v5, 0
	v_mov_b32_e32 v4, 0
	v_mov_b32_e32 v3, 0
	v_mov_b32_e32 v2, 0
	v_mov_b32_e32 v1, 0
	v_mov_b32_e32 v0, 0
	s_cbranch_scc0 .LBB0_564
	v_lshl_add_u64 v[0:1], v[166:167], 0, v[186:187]
	s_add_u32 s0, s18, s0
	global_load_dwordx4 v[96:99], v[0:1], off nt
	global_load_dwordx4 v[100:103], v[0:1], off offset:32 nt
	global_load_dwordx4 v[104:107], v[0:1], off offset:64 nt
	global_load_dwordx4 v[108:111], v[0:1], off offset:96 nt
	v_mov_b32_e32 v1, s20
	v_or_b32_e32 v0, s17, v170
	s_addc_u32 s1, s19, s1
	v_lshlrev_b64 v[0:1], 10, v[0:1]
	s_add_u32 s0, s0, 0xfffffe00
	v_lshl_add_u64 v[0:1], v[166:167], 0, v[0:1]
	s_addc_u32 s1, s1, -1
	global_load_dwordx4 v[112:115], v[0:1], off nt
	global_load_dwordx4 v[116:119], v[0:1], off offset:32 nt
	global_load_dwordx4 v[120:123], v[0:1], off offset:64 nt
	global_load_dwordx4 v[124:127], v[0:1], off offset:96 nt
	v_mov_b32_e32 v1, s1
	v_or_b32_e32 v0, s0, v164
	v_lshlrev_b64 v[0:1], 10, v[0:1]
	v_lshl_add_u64 v[190:191], v[172:173], 0, v[0:1]
	v_lshl_add_u64 v[0:1], s[0:1], 0, v[174:175]
	v_lshlrev_b64 v[0:1], 10, v[0:1]
	v_lshl_add_u64 v[192:193], v[176:177], 0, v[0:1]
	s_lshl_b64 s[0:1], s[44:45], 15
	v_lshl_add_u64 v[0:1], v[192:193], 0, s[0:1]
	v_add_co_u32_e32 v2, vcc, s75, v0
	v_mov_b32_e32 v14, v168
	s_nop 0
	v_addc_co_u32_e32 v3, vcc, 0, v1, vcc
	v_add_co_u32_e32 v4, vcc, s76, v0
	v_mov_b32_e32 v15, v168
	s_nop 0
	v_addc_co_u32_e32 v5, vcc, 0, v1, vcc
	v_add_co_u32_e32 v6, vcc, s77, v0
	v_mov_b32_e32 v169, v168
	s_nop 0
	v_addc_co_u32_e32 v7, vcc, 0, v1, vcc
	global_load_dwordx4 v[152:155], v[4:5], off
	global_load_dwordx4 v[148:151], v[6:7], off
	global_load_dwordx4 v[156:159], v[2:3], off
	global_load_dwordx4 v[144:147], v[0:1], off
	v_lshl_add_u64 v[0:1], v[190:191], 0, s[0:1]
	global_load_dwordx4 v[128:131], v[0:1], off offset:96
	global_load_dwordx4 v[132:135], v[0:1], off offset:64
	global_load_dwordx4 v[136:139], v[0:1], off offset:32
	global_load_dwordx4 v[140:143], v[0:1], off
	v_and_b32_e32 v1, 64, v233
	v_xor_b32_e32 v0, 32, v233
	v_add_u32_e32 v1, 64, v1
	v_cmp_lt_i32_e32 vcc, v0, v1
	s_lshl_b32 s0, s44, 5
	v_mov_b32_e32 v1, v168
	v_cndmask_b32_e32 v0, v233, v0, vcc
	v_lshlrev_b32_e32 v234, 2, v0
	v_mov_b32_e32 v0, v168
	v_mov_b32_e32 v2, v168
	v_mov_b32_e32 v3, v168
	v_mov_b32_e32 v4, v168
	v_mov_b32_e32 v5, v168
	v_mov_b32_e32 v6, v168
	v_mov_b32_e32 v7, v168
	v_mov_b32_e32 v8, v168
	v_mov_b32_e32 v9, v168
	v_mov_b32_e32 v10, v168
	v_mov_b32_e32 v11, v168
	v_mov_b32_e32 v12, v168
	v_mov_b32_e32 v13, v168
	v_mov_b64_e32 v[46:47], v[14:15]
	v_mov_b64_e32 v[30:31], v[14:15]
	v_mov_b64_e32 v[62:63], v[14:15]
	v_subrev_u32_e32 v235, s0, v230
	s_add_i32 s17, s44, -1
	v_mov_b32_e32 v236, 0xff800000
	v_mov_b64_e32 v[44:45], v[12:13]
	v_mov_b64_e32 v[42:43], v[10:11]
	v_mov_b64_e32 v[40:41], v[8:9]
	v_mov_b64_e32 v[38:39], v[6:7]
	v_mov_b64_e32 v[36:37], v[4:5]
	v_mov_b64_e32 v[34:35], v[2:3]
	v_mov_b64_e32 v[32:33], v[0:1]
	v_mov_b64_e32 v[28:29], v[12:13]
	v_mov_b64_e32 v[26:27], v[10:11]
	v_mov_b64_e32 v[24:25], v[8:9]
	v_mov_b64_e32 v[22:23], v[6:7]
	v_mov_b64_e32 v[20:21], v[4:5]
	v_mov_b64_e32 v[18:19], v[2:3]
	v_mov_b64_e32 v[16:17], v[0:1]
	v_mov_b64_e32 v[60:61], v[12:13]
	v_mov_b64_e32 v[58:59], v[10:11]
	v_mov_b64_e32 v[56:57], v[8:9]
	v_mov_b64_e32 v[54:55], v[6:7]
	v_mov_b64_e32 v[52:53], v[4:5]
	v_mov_b64_e32 v[50:51], v[2:3]
	v_mov_b64_e32 v[48:49], v[0:1]
	v_mov_b32_e32 v237, 0xff800000
	v_mov_b64_e32 v[188:189], v[168:169]
	s_branch .LBB0_556
